# g19 + P8 gate/up GEMM tiles distributed dynamically per XCD (linear per-XCD atomic tile counter preserving supertile order, prefetched at tile start, LDS broadcast at latch)
# baseline (speedup 1.0000x reference)
; template <class F> DI void for_tiles_st(int ntm, int ntn, const Sched& sc, F f) {
;     ...
;     const int nsn = ntn >> 2, nsuper = (ntm >> 4) * nsn;
;     for (int sp = sc.xd; sp < nsuper; sp += sc.nx) {
;       const int sm = sp / nsn, sn = sp - sm * nsn;
;       for (int qq = sc.rank; qq < 64; qq += sc.nloc) f(sm * 16 + (qq >> 2), sn * 4 + (qq & 3));
; DI void phase8(const Params& p, const Sched& sched, unsigned char* smem) {
;   XBlk xl{(const u16*)(p.ws + OFF_HBUF), Tn};
;   u16* act = (u16*)(p.ws + OFF_ACT);
;   float* gside = (float*)(p.ws + OFF_GSIDE); float* uside = (float*)(p.ws + OFF_USIDE);
;   float* gl = (float*)smem;
;   for_tiles_st(256, 44, sched, [&](int tm, int tn) {
;     gemm_tile<8>((const u16*)(p.ws + OFF_WGU), 5632, tn * 128, tm * 256, 1024, xl, [&](f32x4 (&acc)[4][8], int fb, int tb, int lr, int lq, int wf, int wt) {
.LBB0_938:
	s_or_b64 exec, exec, s[0:1]
	s_add_u32 s8, s42, 0xbb00800
	s_addc_u32 s9, s43, 0
	s_add_u32 s10, s42, 0x35100800
	s_addc_u32 s11, s43, 0
	s_cmpk_gt_i32 s74, 0xaf
	s_waitcnt lgkmcnt(0)
	s_barrier
	s_cbranch_scc1 .LBB0_974
	s_add_u32 s18, s42, 0x3f00800
	s_addc_u32 s19, s43, 0
	s_cmp_lt_i32 s75, 64
	s_cselect_b64 s[0:1], -1, 0
	s_add_u32 s20, s42, 0xc58000
	s_addc_u32 s21, s43, 0
	s_add_u32 s22, s68, 0x2c00
	s_addc_u32 s23, s69, 0
	v_cndmask_b32_e64 v0, 0, 1, s[0:1]
	s_add_u32 s24, s68, 0x5800
	s_addc_u32 s25, s69, 0
	s_lshl_b32 s33, s74, 2
	s_lshl_b32 s36, s79, 2
	v_cmp_ne_u32_e64 s[0:1], 1, v0
	v_mov_b32_e32 v153, 0
	s_movk_i32 s37, 0xc0
	s_movk_i32 s44, 0x80
	s_mov_b32 s45, 0xcb0000
	s_mov_b32 s46, 0x4300000
	s_mov_b64 s[26:27], 0x400000
	s_mov_b64 s[28:29], 0x58000
	s_movk_i32 s47, 0x90
	s_movk_i32 s48, 0x2c00
	s_movk_i32 s49, 0xfd
	v_mov_b32_e32 v160, 0x900
	v_mov_b32_e32 v161, 0x1200
	v_mov_b32_e32 v162, 0x1b00
	v_mov_b32_e32 v163, 0x2400
	v_mov_b32_e32 v164, 0x2d00
	v_mov_b32_e32 v165, 0x3600
	v_mov_b32_e32 v166, 0x3f00
	v_mov_b32_e32 v167, 0x2c00
	s_mov_b32 s98, s75
	s_mov_b32 s50, -1
	s_branch .Lp8_dyn_decode_n

; template <class F> DI void for_tiles_st(int ntm, int ntn, const Sched& sc, F f) {
;     ...
;     const int nsn = ntn >> 2, nsuper = (ntm >> 4) * nsn;
;     for (int sp = sc.xd; sp < nsuper; sp += sc.nx) {
;       const int sm = sp / nsn, sn = sp - sm * nsn;
;       for (int qq = sc.rank; qq < 64; qq += sc.nloc) f(sm * 16 + (qq >> 2), sn * 4 + (qq & 3));
.Lp8_dyn_recompute:
	s_mul_hi_i32 s4, s50, 0x2e8ba2e9
	s_lshr_b32 s5, s4, 31
	s_ashr_i32 s4, s4, 1
	s_add_i32 s4, s4, s5
	s_mul_i32 s5, s4, -11
	s_add_i32 s5, s5, s50
	s_lshl_b32 s51, s4, 4
	s_mul_i32 s4, s4, 44
	s_lshl_b32 s52, s5, 2
	s_sub_i32 s53, s33, s4
	s_branch .LBB0_944
.LBB0_943:
	s_or_b64 exec, exec, s[4:5]
	v_mov_b32_e32 v243, 0x12000
	v_readfirstlane_b32 s98, v218
	s_cmp_lg_u32 s98, 0
	s_cbranch_scc1 .Lp8_dyn_skip_b
	s_waitcnt vmcnt(12)
	s_mov_b64 s[100:101], exec
	s_mov_b64 exec, 1
	ds_write_b32 v243, v240
	s_waitcnt lgkmcnt(0)
	s_mov_b64 exec, s[100:101]
.Lp8_dyn_skip_b:
	s_barrier
	ds_read_b32 v240, v243
	s_waitcnt lgkmcnt(0)
	v_readfirstlane_b32 s98, v240
	s_add_i32 s98, s98, s78
.Lp8_dyn_decode_n:
	s_and_b32 s55, s98, 63
	s_mov_b32 s54, s55
	s_lshr_b32 s99, s98, 6
	s_mul_i32 s99, s99, s79
	s_add_i32 s99, s99, s74
	s_cmpk_gt_i32 s99, 0xaf
	s_cbranch_scc1 .LBB0_974
	s_cmp_eq_u32 s99, s50
	s_cbranch_scc1 .LBB0_944
	s_mov_b32 s50, s99
	s_lshl_b32 s33, s50, 2
	s_branch .Lp8_dyn_recompute
.LBB0_944:
	v_readfirstlane_b32 s4, v218
	s_cmp_lg_u32 s4, 0
	s_cbranch_scc1 .Lp8_dyn_skip_a
	s_mov_b64 s[100:101], exec
	s_mov_b64 exec, 1
	v_mov_b32_e32 v241, 0x3fb04100
	v_lshl_add_u32 v241, s74, 6, v241
	v_mov_b32_e32 v242, 1
	global_atomic_add v240, v241, v242, s[42:43] sc0
	s_mov_b64 exec, s[100:101]
